# stack: hyena prologue prefetch + zero-block reads + software-pipelined main MFMA loop; last-layer tile-local residual add (no final grid barrier), 8 row groups in flight
# speedup vs baseline: 1.0146x; 1.0043x over previous
; __device__ __forceinline__ void phase_hyena(int l, LAS unsigned char* lds, int G) {
;     ...
;         { int D = Dlo;
;           for (; D < 8 * wave - 59; ++D) HY_BODY(true, false);
;           for (; D <= 8 * wave + 3; ++D) HY_BODY(true, true);
.LBB0_535:
	v_add_u32_e32 v156, v155, v128
	v_add_u32_e32 v156, 0x12040, v156
	ds_read2_b32 v[80:81], v156 offset0:0 offset1:1
	ds_read2_b32 v[82:83], v156 offset0:2 offset1:3
	ds_read2_b32 v[6:7], v156 offset0:8 offset1:9
	ds_read2_b32 v[8:9], v156 offset0:10 offset1:11
	ds_read2_b32 v[10:11], v156 offset0:16 offset1:17
	ds_read2_b32 v[12:13], v156 offset0:18 offset1:19
	ds_read2_b32 v[2:3], v156 offset0:24 offset1:25
	ds_read2_b32 v[4:5], v156 offset0:26 offset1:27
	ds_read2_b32 v[88:89], v156 offset0:32 offset1:33
	ds_read2_b32 v[90:91], v156 offset0:34 offset1:35
	ds_read2_b32 v[84:85], v156 offset0:40 offset1:41
	ds_read2_b32 v[86:87], v156 offset0:42 offset1:43
	v_cmp_gt_u32_e32 vcc, 64, v15
	v_add_u32_e32 v157, v14, v128
	v_add_u32_e32 v159, 4, v15
	v_cndmask_b32_e32 v157, v227, v157, vcc
	ds_read_b128 v[92:95], v157
	ds_read_b128 v[100:103], v157 offset:32
	ds_read_b128 v[96:99], v157 offset:64
	ds_read_b128 v[104:107], v157 offset:96
	v_cmp_gt_u32_e32 vcc, 64, v159
	v_add_u32_e32 v158, v0, v128
	s_nop 0
	v_cndmask_b32_e32 v158, v227, v158, vcc
	ds_read_b128 v[108:111], v158
	ds_read_b128 v[116:119], v158 offset:32
	ds_read_b128 v[112:115], v158 offset:64
	ds_read_b128 v[120:123], v158 offset:96
.Lhy_x:
	s_waitcnt lgkmcnt(0)
	s_cmp_ge_i32 s2, s78
	s_cbranch_scc1 .Lhy_x_last
	v_add_u32_e32 v155, 0xffffff80, v155
	v_add_u32_e32 v15, -1, v15
	v_add_u32_e32 v14, 0xffffff80, v14
	v_add_u32_e32 v0, 0xffffff80, v0
	s_add_i32 s2, s2, 1
	v_add_u32_e32 v156, v155, v128
	v_add_u32_e32 v156, 0x12040, v156
	ds_read2_b32 v[160:161], v156 offset0:0 offset1:1
	ds_read2_b32 v[162:163], v156 offset0:2 offset1:3
	ds_read2_b32 v[164:165], v156 offset0:8 offset1:9
	ds_read2_b32 v[166:167], v156 offset0:10 offset1:11
	ds_read2_b32 v[168:169], v156 offset0:16 offset1:17
	ds_read2_b32 v[170:171], v156 offset0:18 offset1:19
	ds_read2_b32 v[172:173], v156 offset0:24 offset1:25
	ds_read2_b32 v[174:175], v156 offset0:26 offset1:27
	ds_read2_b32 v[176:177], v156 offset0:32 offset1:33
	ds_read2_b32 v[178:179], v156 offset0:34 offset1:35
	ds_read2_b32 v[180:181], v156 offset0:40 offset1:41
	ds_read2_b32 v[182:183], v156 offset0:42 offset1:43
	v_cmp_gt_u32_e32 vcc, 64, v15
	v_add_u32_e32 v157, v14, v128
	v_add_u32_e32 v159, 4, v15
	v_cndmask_b32_e32 v157, v227, v157, vcc
	ds_read_b128 v[184:187], v157
	ds_read_b128 v[204:207], v157 offset:32
	ds_read_b128 v[208:211], v157 offset:64
	ds_read_b128 v[212:215], v157 offset:96
	v_cmp_gt_u32_e32 vcc, 64, v159
	v_add_u32_e32 v158, v0, v128
	s_nop 0
	v_cndmask_b32_e32 v158, v227, v158, vcc
	ds_read_b128 v[228:231], v158
	ds_read_b128 v[232:235], v158 offset:32
	ds_read_b128 v[236:239], v158 offset:64
	ds_read_b128 v[240:243], v158 offset:96
	s_setprio 1
	v_mfma_f32_32x32x16_bf16 v[48:63], v[10:13], v[92:95], v[48:63]
	v_mfma_f32_32x32x16_bf16 v[64:79], v[10:13], v[108:111], v[64:79]
	v_mfma_f32_32x32x16_bf16 v[16:31], v[80:83], v[92:95], v[16:31]
	v_mfma_f32_32x32x16_bf16 v[32:47], v[80:83], v[108:111], v[32:47]
	v_mfma_f32_32x32x16_bf16 v[48:63], v[2:5], v[100:103], v[48:63]
	v_mfma_f32_32x32x16_bf16 v[64:79], v[2:5], v[116:119], v[64:79]
	v_mfma_f32_32x32x16_bf16 v[16:31], v[6:9], v[100:103], v[16:31]
	v_mfma_f32_32x32x16_bf16 v[32:47], v[6:9], v[116:119], v[32:47]
	v_mfma_f32_32x32x16_bf16 v[48:63], v[88:91], v[96:99], v[48:63]
	v_mfma_f32_32x32x16_bf16 v[64:79], v[88:91], v[112:115], v[64:79]
	v_mfma_f32_32x32x16_bf16 v[16:31], v[10:13], v[96:99], v[16:31]
	v_mfma_f32_32x32x16_bf16 v[32:47], v[10:13], v[112:115], v[32:47]
	v_mfma_f32_32x32x16_bf16 v[48:63], v[84:87], v[104:107], v[48:63]
	v_mfma_f32_32x32x16_bf16 v[64:79], v[84:87], v[120:123], v[64:79]
	v_mfma_f32_32x32x16_bf16 v[16:31], v[2:5], v[104:107], v[16:31]
	v_mfma_f32_32x32x16_bf16 v[32:47], v[2:5], v[120:123], v[32:47]
	s_setprio 0
	s_waitcnt lgkmcnt(0)
	s_cmp_ge_i32 s2, s78
	s_cbranch_scc1 .Lhy_y_last
	v_add_u32_e32 v155, 0xffffff80, v155
	v_add_u32_e32 v15, -1, v15
	v_add_u32_e32 v14, 0xffffff80, v14
	v_add_u32_e32 v0, 0xffffff80, v0
	s_add_i32 s2, s2, 1
	v_add_u32_e32 v156, v155, v128
	v_add_u32_e32 v156, 0x12040, v156
	ds_read2_b32 v[80:81], v156 offset0:0 offset1:1
	ds_read2_b32 v[82:83], v156 offset0:2 offset1:3
	ds_read2_b32 v[6:7], v156 offset0:8 offset1:9
	ds_read2_b32 v[8:9], v156 offset0:10 offset1:11
	ds_read2_b32 v[10:11], v156 offset0:16 offset1:17
	ds_read2_b32 v[12:13], v156 offset0:18 offset1:19
	ds_read2_b32 v[2:3], v156 offset0:24 offset1:25
	ds_read2_b32 v[4:5], v156 offset0:26 offset1:27
	ds_read2_b32 v[88:89], v156 offset0:32 offset1:33
	ds_read2_b32 v[90:91], v156 offset0:34 offset1:35
	ds_read2_b32 v[84:85], v156 offset0:40 offset1:41
	ds_read2_b32 v[86:87], v156 offset0:42 offset1:43
	v_cmp_gt_u32_e32 vcc, 64, v15
	v_add_u32_e32 v157, v14, v128
	v_add_u32_e32 v159, 4, v15
	v_cndmask_b32_e32 v157, v227, v157, vcc
	ds_read_b128 v[92:95], v157
	ds_read_b128 v[100:103], v157 offset:32
	ds_read_b128 v[96:99], v157 offset:64
	ds_read_b128 v[104:107], v157 offset:96
	v_cmp_gt_u32_e32 vcc, 64, v159
	v_add_u32_e32 v158, v0, v128
	s_nop 0
	v_cndmask_b32_e32 v158, v227, v158, vcc
	ds_read_b128 v[108:111], v158
	ds_read_b128 v[116:119], v158 offset:32
	ds_read_b128 v[112:115], v158 offset:64
	ds_read_b128 v[120:123], v158 offset:96
	s_setprio 1
	v_mfma_f32_32x32x16_bf16 v[48:63], v[168:171], v[184:187], v[48:63]
	v_mfma_f32_32x32x16_bf16 v[64:79], v[168:171], v[228:231], v[64:79]
	v_mfma_f32_32x32x16_bf16 v[16:31], v[160:163], v[184:187], v[16:31]
	v_mfma_f32_32x32x16_bf16 v[32:47], v[160:163], v[228:231], v[32:47]
	v_mfma_f32_32x32x16_bf16 v[48:63], v[172:175], v[204:207], v[48:63]
	v_mfma_f32_32x32x16_bf16 v[64:79], v[172:175], v[232:235], v[64:79]
	v_mfma_f32_32x32x16_bf16 v[16:31], v[164:167], v[204:207], v[16:31]
	v_mfma_f32_32x32x16_bf16 v[32:47], v[164:167], v[232:235], v[32:47]
	v_mfma_f32_32x32x16_bf16 v[48:63], v[176:179], v[208:211], v[48:63]
	v_mfma_f32_32x32x16_bf16 v[64:79], v[176:179], v[236:239], v[64:79]
	v_mfma_f32_32x32x16_bf16 v[16:31], v[168:171], v[208:211], v[16:31]
	v_mfma_f32_32x32x16_bf16 v[32:47], v[168:171], v[236:239], v[32:47]
	v_mfma_f32_32x32x16_bf16 v[48:63], v[180:183], v[212:215], v[48:63]
	v_mfma_f32_32x32x16_bf16 v[64:79], v[180:183], v[240:243], v[64:79]
	v_mfma_f32_32x32x16_bf16 v[16:31], v[172:175], v[212:215], v[16:31]
	v_mfma_f32_32x32x16_bf16 v[32:47], v[172:175], v[240:243], v[32:47]
	s_setprio 0
	s_branch .Lhy_x
; __device__ __forceinline__ void phase_hyena(int l, LAS unsigned char* lds, int G) {
;     ...
;         { int D = Dlo;
;           for (; D < 8 * wave - 59; ++D) HY_BODY(true, false);
;           for (; D <= 8 * wave + 3; ++D) HY_BODY(true, true);
;           for (; D <= Dhi; ++D) HY_BODY(false, true); }
.Lhy_x_last:
	s_setprio 1
	v_mfma_f32_32x32x16_bf16 v[48:63], v[10:13], v[92:95], v[48:63]
	v_mfma_f32_32x32x16_bf16 v[64:79], v[10:13], v[108:111], v[64:79]
	v_mfma_f32_32x32x16_bf16 v[16:31], v[80:83], v[92:95], v[16:31]
	v_mfma_f32_32x32x16_bf16 v[32:47], v[80:83], v[108:111], v[32:47]
	v_mfma_f32_32x32x16_bf16 v[48:63], v[2:5], v[100:103], v[48:63]
	v_mfma_f32_32x32x16_bf16 v[64:79], v[2:5], v[116:119], v[64:79]
	v_mfma_f32_32x32x16_bf16 v[16:31], v[6:9], v[100:103], v[16:31]
	v_mfma_f32_32x32x16_bf16 v[32:47], v[6:9], v[116:119], v[32:47]
	v_mfma_f32_32x32x16_bf16 v[48:63], v[88:91], v[96:99], v[48:63]
	v_mfma_f32_32x32x16_bf16 v[64:79], v[88:91], v[112:115], v[64:79]
	v_mfma_f32_32x32x16_bf16 v[16:31], v[10:13], v[96:99], v[16:31]
	v_mfma_f32_32x32x16_bf16 v[32:47], v[10:13], v[112:115], v[32:47]
	v_mfma_f32_32x32x16_bf16 v[48:63], v[84:87], v[104:107], v[48:63]
	v_mfma_f32_32x32x16_bf16 v[64:79], v[84:87], v[120:123], v[64:79]
	v_mfma_f32_32x32x16_bf16 v[16:31], v[2:5], v[104:107], v[16:31]
	v_mfma_f32_32x32x16_bf16 v[32:47], v[2:5], v[120:123], v[32:47]
	s_setprio 0
	s_branch .Lhy_done
.Lhy_y_last:
	s_setprio 1
	v_mfma_f32_32x32x16_bf16 v[48:63], v[168:171], v[184:187], v[48:63]
	v_mfma_f32_32x32x16_bf16 v[64:79], v[168:171], v[228:231], v[64:79]
	v_mfma_f32_32x32x16_bf16 v[16:31], v[160:163], v[184:187], v[16:31]
	v_mfma_f32_32x32x16_bf16 v[32:47], v[160:163], v[228:231], v[32:47]
	v_mfma_f32_32x32x16_bf16 v[48:63], v[172:175], v[204:207], v[48:63]
	v_mfma_f32_32x32x16_bf16 v[64:79], v[172:175], v[232:235], v[64:79]
	v_mfma_f32_32x32x16_bf16 v[16:31], v[164:167], v[204:207], v[16:31]
	v_mfma_f32_32x32x16_bf16 v[32:47], v[164:167], v[232:235], v[32:47]
	v_mfma_f32_32x32x16_bf16 v[48:63], v[176:179], v[208:211], v[48:63]
	v_mfma_f32_32x32x16_bf16 v[64:79], v[176:179], v[236:239], v[64:79]
	v_mfma_f32_32x32x16_bf16 v[16:31], v[168:171], v[208:211], v[16:31]
	v_mfma_f32_32x32x16_bf16 v[32:47], v[168:171], v[236:239], v[32:47]
	v_mfma_f32_32x32x16_bf16 v[48:63], v[180:183], v[212:215], v[48:63]
	v_mfma_f32_32x32x16_bf16 v[64:79], v[180:183], v[240:243], v[64:79]
	v_mfma_f32_32x32x16_bf16 v[16:31], v[172:175], v[212:215], v[16:31]
	v_mfma_f32_32x32x16_bf16 v[32:47], v[172:175], v[240:243], v[32:47]
	s_setprio 0
.Lhy_done:
	s_add_i32 s2, s2, 1
	s_branch .LBB0_521
